# forgetting-attention loop role A: staging stores and next loads moved after the softmax as in the differential loop
# baseline (speedup 1.0000x reference)
; __device__ __forceinline__ s16x4 vtr(ldsp p) { return __builtin_bit_cast(s16x4, __builtin_amdgcn_ds_read_tr16_b64_v4i16((LAS v4i16_t*)p)); }
; #define MASK_BLOCK() do { if (kt == 0 || kt >= diag0) { \
;             _Pragma("unroll") for (int r = 0; r < 16; ++r) { const int kpp = 64 * kt + crow(r, hi); \
;                 if (kpp < 48 || kpp > q_pp) s0[r] = -INFINITY; \
;                 if (kpp + 32 < 48 || kpp + 32 > q_pp) s1[r] = -INFINITY; } } } while (0)
; #define EXPSUM_BLOCK() do { psa = 0.f; psb = 0.f; \
;             _Pragma("unroll") for (int r = 0; r < 16; ++r) { s0[r] = __builtin_amdgcn_exp2f(s0[r]); s1[r] = __builtin_amdgcn_exp2f(s1[r]); psa += s0[r]; asm("" : "+v"(psa)); psb += s1[r]; asm("" : "+v"(psb)); } } while (0)
; template <bool DIFF>
; __device__ __forceinline__ void attn_unit(const AttnP& A, int b, int h, int qi, ldsp lds) {
;     ...
;             QK_BLOCK();
;             s16x4 vlo[8], vhi[8];
; #pragma unroll
;             for (int t = 0; t < 2; ++t)
; #pragma unroll
;                 for (int j = 0; j < 4; ++j) { vlo[t * 4 + j] = vtr(Vb + trb + (16 * j) * VP + t * 64); vhi[t * 4 + j] = vtr(Vb + trb + (16 * j + 8) * VP + t * 64); }
;             __builtin_amdgcn_sched_barrier(0);
;             MASK_BLOCK();
;             bool full = (kt == kt0);
;             float psa, psb;
;             if (!full) {
;                 EXPSUM_BLOCK();
;                 if (__any(psa + psb > 1.0e18f)) { full = true; QK_BLOCK();
;     ...
;             __builtin_amdgcn_s_setprio(1);
; #pragma unroll
;             for (int t = 0; t < 2; ++t)
; #pragma unroll
;                 for (int j = 0; j < 4; ++j) {
;                     const bf16x8 vf = (bf16x8){vlo[t * 4 + j][0], vlo[t * 4 + j][1], vlo[t * 4 + j][2], vlo[t * 4 + j][3], vhi[t * 4 + j][0], vhi[t * 4 + j][1], vhi[t * 4 + j][2], vhi[t * 4 + j][3]};
;                     o[t] = __builtin_amdgcn_mfma_f32_32x32x16_bf16(vf, pw[j], o[t], 0, 0, 0);
;                 }
.Lfa_s_top:
	s_bitcmp1_b32 s99, 0
	s_cselect_b32 s74, 0x5500, 0
	s_sub_i32 s75, 0x5500, s74
	v_add_u32_e32 v169, s74, v150
	v_add_u32_e32 v0, s74, v164
	v_add_u32_e32 v168, s75, v161
	ds_read_b64_tr_b16 v[106:107], v168 offset:9216
	ds_read_b64_tr_b16 v[108:109], v168 offset:10752
	ds_read_b64_tr_b16 v[110:111], v168 offset:9280
	ds_read_b64_tr_b16 v[112:113], v168 offset:10816
	ds_read_b64_tr_b16 v[116:117], v168 offset:12288
	ds_read_b64_tr_b16 v[118:119], v168 offset:13824
	ds_read_b64_tr_b16 v[120:121], v168 offset:12352
	ds_read_b64_tr_b16 v[122:123], v168 offset:13888
	ds_read_b64_tr_b16 v[124:125], v168 offset:15360
	ds_read_b64_tr_b16 v[126:127], v168 offset:16896
	ds_read_b64_tr_b16 v[128:129], v168 offset:15424
	ds_read_b64_tr_b16 v[130:131], v168 offset:16960
	ds_read_b64_tr_b16 v[132:133], v168 offset:18432
	ds_read_b64_tr_b16 v[134:135], v168 offset:19968
	ds_read_b64_tr_b16 v[136:137], v168 offset:18496
	ds_read_b64_tr_b16 v[138:139], v168 offset:20032
	v_mov_b32_e32 v248, s97
	ds_read_b32 v248, v248
	ds_read_b128 v[170:173], v169
	ds_read_b128 v[244:247], v169 offset:4608
	s_waitcnt lgkmcnt(15)
	v_mfma_f32_32x32x16_bf16 v[18:33], v[106:109], v[66:69], v[18:33]
	ds_read_b128 v[106:109], v169 offset:32
	s_waitcnt lgkmcnt(15)
	v_mfma_f32_32x32x16_bf16 v[2:17], v[110:113], v[66:69], v[2:17]
	ds_read_b128 v[110:113], v169 offset:4640
	s_waitcnt lgkmcnt(15)
	v_mfma_f32_32x32x16_bf16 v[18:33], v[116:119], v[70:73], v[18:33]
	ds_read_b128 v[116:119], v169 offset:64
	s_waitcnt lgkmcnt(14)
	v_mfma_f32_32x32x16_bf16 v[2:17], v[120:123], v[70:73], v[2:17]
	ds_read_b128 v[120:123], v169 offset:4672
	s_waitcnt lgkmcnt(13)
	v_mfma_f32_32x32x16_bf16 v[18:33], v[124:127], v[50:53], v[18:33]
	ds_read_b128 v[124:127], v169 offset:96
	s_waitcnt lgkmcnt(12)
	v_mfma_f32_32x32x16_bf16 v[2:17], v[128:131], v[50:53], v[2:17]
	ds_read_b128 v[128:131], v169 offset:4704
	s_waitcnt lgkmcnt(11)
	v_mfma_f32_32x32x16_bf16 v[18:33], v[132:135], v[54:57], v[18:33]
	ds_read_b128 v[132:135], v0 offset:128
	s_waitcnt lgkmcnt(10)
	v_mfma_f32_32x32x16_bf16 v[2:17], v[136:139], v[54:57], v[2:17]
	ds_read_b128 v[136:139], v0 offset:4736
	s_waitcnt lgkmcnt(9)
	v_mfma_f32_32x32x16_bf16 v[66:81], v[170:173], v[90:93], v[34:49]
	s_waitcnt lgkmcnt(8)
	v_mfma_f32_32x32x16_bf16 v[50:65], v[244:247], v[90:93], v[34:49]
	v_sub_f32_e32 v249, v160, v248
	v_cvt_pk_bf16_f32 v162, v249, 0
	v_lshlrev_b32_e32 v162, 16, v162
	s_waitcnt lgkmcnt(7)
	v_mfma_f32_32x32x16_bf16 v[66:81], v[106:109], v[82:85], v[66:81]
	s_waitcnt lgkmcnt(6)
	v_mfma_f32_32x32x16_bf16 v[50:65], v[110:113], v[82:85], v[50:65]
	v_sub_f32_e32 v249, v249, v162
	v_cvt_pk_bf16_f32 v163, v249, 0
	v_and_b32_e32 v157, 0xffff, v163
	v_lshlrev_b32_e32 v163, 16, v163
	s_waitcnt lgkmcnt(5)
	v_mfma_f32_32x32x16_bf16 v[66:81], v[116:119], v[86:89], v[66:81]
	s_waitcnt lgkmcnt(4)
	v_mfma_f32_32x32x16_bf16 v[50:65], v[120:123], v[86:89], v[50:65]
	v_sub_f32_e32 v249, v249, v163
	v_cvt_pk_bf16_f32 v249, v249, 0
	v_or_b32_e32 v162, 0x3f80, v162
	v_lshl_or_b32 v249, v249, 16, v157
	v_cndmask_b32_e64 v140, 0, v114, s[46:47]
	v_cndmask_b32_e64 v142, 0, v249, s[46:47]
	v_cndmask_b32_e64 v141, 0, v162, s[46:47]
	v_mov_b32_e32 v143, v1
	s_waitcnt lgkmcnt(3)
	v_mfma_f32_32x32x16_bf16 v[66:81], v[124:127], v[94:97], v[66:81]
	s_waitcnt lgkmcnt(2)
	v_mfma_f32_32x32x16_bf16 v[50:65], v[128:131], v[94:97], v[50:65]
	s_waitcnt lgkmcnt(1)
	v_mfma_f32_32x32x16_bf16 v[66:81], v[132:135], v[140:143], v[66:81]
	s_waitcnt lgkmcnt(0)
	v_mfma_f32_32x32x16_bf16 v[50:65], v[136:139], v[140:143], v[50:65]
	s_nop 7
	s_nop 3
	v_exp_f32_e32 v106, v66
	v_exp_f32_e32 v124, v50
	v_exp_f32_e32 v107, v67
	v_exp_f32_e32 v125, v51
	v_add_f32_e32 v166, 0, v106
	v_add_f32_e32 v167, 0, v124
	v_exp_f32_e32 v108, v68
	v_exp_f32_e32 v126, v52
	v_add_f32_e32 v166, v107, v166
	v_add_f32_e32 v167, v125, v167
	v_exp_f32_e32 v109, v69
	v_exp_f32_e32 v127, v53
	v_add_f32_e32 v166, v108, v166
	v_add_f32_e32 v167, v126, v167
	v_exp_f32_e32 v110, v70
	v_exp_f32_e32 v128, v54
	v_add_f32_e32 v166, v109, v166
	v_add_f32_e32 v167, v127, v167
	v_exp_f32_e32 v111, v71
	v_exp_f32_e32 v129, v55
	v_add_f32_e32 v166, v110, v166
	v_add_f32_e32 v167, v128, v167
	v_exp_f32_e32 v112, v72
	v_exp_f32_e32 v130, v56
	v_add_f32_e32 v166, v111, v166
	v_add_f32_e32 v167, v129, v167
	v_exp_f32_e32 v113, v73
	v_exp_f32_e32 v131, v57
	v_add_f32_e32 v166, v112, v166
	v_add_f32_e32 v167, v130, v167
	v_exp_f32_e32 v116, v74
	v_exp_f32_e32 v132, v58
	v_add_f32_e32 v166, v113, v166
	v_add_f32_e32 v167, v131, v167
	v_exp_f32_e32 v117, v75
	v_exp_f32_e32 v133, v59
	v_add_f32_e32 v166, v116, v166
	v_add_f32_e32 v167, v132, v167
	v_exp_f32_e32 v118, v76
	v_exp_f32_e32 v134, v60
	v_add_f32_e32 v166, v117, v166
	v_add_f32_e32 v167, v133, v167
	v_exp_f32_e32 v119, v77
	v_exp_f32_e32 v135, v61
	v_add_f32_e32 v166, v118, v166
	v_add_f32_e32 v167, v134, v167
	v_exp_f32_e32 v120, v78
	v_exp_f32_e32 v136, v62
	v_add_f32_e32 v166, v119, v166
	v_add_f32_e32 v167, v135, v167
	v_exp_f32_e32 v121, v79
	v_exp_f32_e32 v137, v63
	v_add_f32_e32 v166, v120, v166
	v_add_f32_e32 v167, v136, v167
	v_exp_f32_e32 v122, v80
	v_exp_f32_e32 v138, v64
	v_add_f32_e32 v166, v121, v166
	v_add_f32_e32 v167, v137, v167
	v_exp_f32_e32 v123, v81
	v_exp_f32_e32 v139, v65
	v_add_f32_e32 v166, v122, v166
	v_add_f32_e32 v167, v138, v167
	s_nop 0
	v_add_f32_e32 v166, v123, v166
	v_add_f32_e32 v167, v139, v167
	v_add_f32_e32 v141, v166, v167
	v_cmp_lt_f32_e32 vcc, s85, v141
	s_cbranch_vccnz .Lfa_s_slow
; __device__ __forceinline__ s16x4 vtr(ldsp p) { return __builtin_bit_cast(s16x4, __builtin_amdgcn_ds_read_tr16_b64_v4i16((LAS v4i16_t*)p)); }
; template <bool DIFF>
; __device__ __forceinline__ void attn_unit(const AttnP& A, int b, int h, int qi, ldsp lds) {
;     ...
;             l_run += psa + psb;
;     ...
;             bf16x8 pw[4];
; #pragma unroll
;             for (int j = 0; j < 4; ++j) {
;                 u32x4 pk;
;                 if (j < 2) { const int rb = 8 * (j & 1); pk.x = cvtpk(s0[rb], s0[rb + 1]); pk.y = cvtpk(s0[rb + 2], s0[rb + 3]); pk.z = cvtpk(s0[rb + 4], s0[rb + 5]); pk.w = cvtpk(s0[rb + 6], s0[rb + 7]); }
;                 else { const int rb = 8 * (j & 1); pk.x = cvtpk(s1[rb], s1[rb + 1]); pk.y = cvtpk(s1[rb + 2], s1[rb + 3]); pk.z = cvtpk(s1[rb + 4], s1[rb + 5]); pk.w = cvtpk(s1[rb + 6], s1[rb + 7]); }
;                 pw[j] = __builtin_bit_cast(bf16x8, pk);
;             }
;             __builtin_amdgcn_sched_barrier(0);
;             __builtin_amdgcn_s_setprio(1);
; #pragma unroll
;             for (int t = 0; t < 2; ++t)
; #pragma unroll
;                 for (int j = 0; j < 4; ++j) {
;                     const bf16x8 vf = (bf16x8){vlo[t * 4 + j][0], vlo[t * 4 + j][1], vlo[t * 4 + j][2], vlo[t * 4 + j][3], vhi[t * 4 + j][0], vhi[t * 4 + j][1], vhi[t * 4 + j][2], vhi[t * 4 + j][3]};
;                     o[t] = __builtin_amdgcn_mfma_f32_32x32x16_bf16(vf, pw[j], o[t], 0, 0, 0);
;                 }
;             if (DIFF) {
; #pragma unroll
;                 for (int t = 2; t < NTD; ++t)
; #pragma unroll
;                     for (int j = 0; j < 4; ++j) { vlo[(t - 2) * 4 + j] = vtr(Vb + trb + (16 * j) * VP + t * 64); vhi[(t - 2) * 4 + j] = vtr(Vb + trb + (16 * j + 8) * VP + t * 64); }
;                 __builtin_amdgcn_sched_barrier(0);
; #pragma unroll
;                 for (int t = 2; t < NTD; ++t)
; #pragma unroll
;                     for (int j = 0; j < 4; ++j) {
;                         const int i = (t - 2) * 4 + j;
;                         const bf16x8 vf = (bf16x8){vlo[i][0], vlo[i][1], vlo[i][2], vlo[i][3], vhi[i][0], vhi[i][1], vhi[i][2], vhi[i][3]};
;                         o[t] = __builtin_amdgcn_mfma_f32_32x32x16_bf16(vf, pw[j], o[t], 0, 0, 0);
;                     }
;             }
;             __builtin_amdgcn_s_setprio(0);
;         }
;         if (kt + 1 < nt) STORE_TILE((kt + 1) & 1);
;         __syncthreads();
;     }
	v_cvt_pk_bf16_f32 v66, v106, v107
	v_cvt_pk_bf16_f32 v67, v108, v109
	v_cvt_pk_bf16_f32 v68, v110, v111
	v_cvt_pk_bf16_f32 v69, v112, v113
	v_cvt_pk_bf16_f32 v70, v116, v117
	v_cvt_pk_bf16_f32 v71, v118, v119
	v_cvt_pk_bf16_f32 v72, v120, v121
	v_cvt_pk_bf16_f32 v73, v122, v123
	v_cvt_pk_bf16_f32 v50, v124, v125
	v_cvt_pk_bf16_f32 v51, v126, v127
	v_cvt_pk_bf16_f32 v52, v128, v129
	v_cvt_pk_bf16_f32 v53, v130, v131
	v_cvt_pk_bf16_f32 v54, v132, v133
	v_cvt_pk_bf16_f32 v55, v134, v135
	v_cvt_pk_bf16_f32 v56, v136, v137
	v_cvt_pk_bf16_f32 v57, v138, v139
	v_add_f32_e32 v154, v141, v154
	s_waitcnt vmcnt(0)
	v_add_u32_e32 v115, s75, v156
	ds_write_b128 v115, v[98:101]
	s_and_saveexec_b64 s[0:1], s[44:45]
	v_xor_b32_e32 v248, 0x80000000, v155
	v_cvt_pk_bf16_f32 v248, v248, 0
	v_lshlrev_b32_e32 v249, 16, v248
	v_sub_f32_e64 v249, -v155, v249
	v_cvt_pk_bf16_f32 v162, v249, 0
	v_lshlrev_b32_e32 v162, 16, v162
	v_sub_f32_e32 v249, v249, v162
	v_cvt_pk_bf16_f32 v249, v249, 0
	v_and_or_b32 v112, v248, s83, v162
	v_and_or_b32 v113, v249, s83, 1.0
	v_mov_b32_e32 v115, v1
	v_add_u32_e32 v248, s75, v159
	ds_write_b128 v248, v[112:115] offset:128
	s_mov_b64 exec, s[0:1]
	v_add_u32_e32 v115, s74, v158
	ds_write_b128 v115, v[102:105] offset:9216
	global_load_dwordx4 v[102:105], v[250:251], off
	v_lshl_add_u64 v[250:251], v[250:251], 0, s[26:27]
	global_load_dwordx4 v[98:101], v[152:153], off
	v_lshl_add_u64 v[152:153], v[152:153], 0, s[26:27]
	s_and_saveexec_b64 s[0:1], s[44:45]
	global_load_dword v155, v[252:253], off
	s_mov_b64 exec, s[0:1]
	s_mov_b64 s[0:1], 0x800
	v_lshl_add_u64 v[252:253], v[252:253], 0, s[0:1]
	s_waitcnt lgkmcnt(0)
	s_barrier
	s_add_i32 s99, s99, 1
	s_add_i32 s94, s94, 1
	s_add_i32 s97, s97, 4
	s_add_i32 s98, s98, 64
	s_add_i32 s0, s95, -1
	s_cmp_le_i32 s99, s0
	s_cbranch_scc1 .Lfa_s_top

; __device__ __forceinline__ unsigned cvtpk(float lo, float hi) { f32x2 v = {lo, hi}; bf16x2_t b = __builtin_convertvector(v, bf16x2_t); return __builtin_bit_cast(unsigned, b); }
; __device__ __forceinline__ void split3(float x, unsigned& h, unsigned& m, unsigned& l) {
;     h = cvtpk(x, 0.f) & 0xffffu; const float r1 = x - __uint_as_float(h << 16);
;     m = cvtpk(r1, 0.f) & 0xffffu; const float r2 = r1 - __uint_as_float(m << 16);
;     l = cvtpk(r2, 0.f) & 0xffffu;
; }
.Lfa_s_slow:
	s_bitcmp1_b32 s99, 0
	s_cselect_b32 s74, 0x5500, 0
	s_sub_i32 s75, 0x5500, s74
	s_waitcnt vmcnt(0)
	s_cmp_ge_i32 s99, s91
	s_cbranch_scc1 .Lfx13_snok
	v_add_u32_e32 v115, s75, v156
	ds_write_b128 v115, v[98:101]
	s_and_saveexec_b64 s[0:1], s[44:45]
	v_xor_b32_e32 v248, 0x80000000, v155
	v_cvt_pk_bf16_f32 v248, v248, 0
	v_lshlrev_b32_e32 v249, 16, v248
	v_sub_f32_e64 v249, -v155, v249
	v_cvt_pk_bf16_f32 v162, v249, 0
	v_lshlrev_b32_e32 v162, 16, v162
	v_sub_f32_e32 v249, v249, v162
	v_cvt_pk_bf16_f32 v249, v249, 0
	v_and_or_b32 v112, v248, s83, v162
	v_and_or_b32 v113, v249, s83, 1.0
	v_mov_b32_e32 v115, v1
	v_add_u32_e32 v248, s75, v159
	ds_write_b128 v248, v[112:115] offset:128
	s_mov_b64 exec, s[0:1]
